# static s_setprio 1 for waves 4-7 in the S3 and MoBA kv phases, placement-preserving (on phase 0 + gate load hoist)
# speedup vs baseline: 1.0122x; 1.0029x over previous
; #define LAS __attribute__((address_space(3)))
; __device__ __forceinline__ void ssd_s3_phase(Frame& F, const bf16* xc, const bf16* xtile, const bf16* btok, const bf16* ctok, const bf16* zx, const float* dt, const float* a_log, const float* dsk, float* ssg, const bf16* states, bf16* ybuf) {
;     const int lane = F.lane, r = lane & 31, h2 = lane >> 5, li = F.wave >> 1, hhalf = F.wave & 1;
;     LAS float* cst = (LAS float*)(F.lds + RING_OFF);
;     LAS float* dtt = cst + 2048;
;     LAS float* ssw = dtt + 2048;
;     LAS float* TT = (LAS float*)(F.lds + RING_OFF + 20480) + F.wave * (32 * 36);
;     const int el = lane >> 1, eh = lane & 1;
;     for (int u = blockIdx.x; u < 64 * SSD_NG; u += F.G) {
;         const int c = u >> 3, g = u & 7, t0 = c * 128;
; #pragma unroll
;         for (int hh = 0; hh < 2; ++hh) { const int hl = F.wave * 2 + hh, h = g * 16 + hl; const float A = -__expf(a_log[h]);
.LBB0_544:
	s_cmpk_ge_u32 s94, 0x100
	s_cbranch_scc0 .Lprio_skip_a
	s_setprio 1

; __device__ __forceinline__ unsigned xb_add(unsigned* p, unsigned v) { return __hip_atomic_fetch_add(p, v, __ATOMIC_RELAXED, __HIP_MEMORY_SCOPE_AGENT); }
; __device__ __forceinline__ void xcd_barrier(const XcdBarrier& b) {
;     asm volatile("s_waitcnt vmcnt(0)" ::: "memory");
;     __syncthreads();
;     if (threadIdx.x == 0) {
;         unsigned* bar = b.bar;
;         __builtin_amdgcn_s_waitcnt(0);
;         unsigned nloc = b.st[0], nx = b.st[1];
;         if (nloc == 0u) { xcd_barrier_complete(bar, b.x, nloc, nx); b.st[0] = nloc; b.st[1] = nx; }
;         const unsigned old = xb_add(&bar[XB_XSUB(b.x)], 1u);
.LBB0_567:
	s_setprio 0
	s_nop 0
	s_nop 0
	s_nop 0
	s_nop 0
	s_nop 0
	s_nop 0
	s_nop 0
	s_nop 0
	s_nop 0
	s_nop 0
	s_nop 0
	s_nop 0
	s_nop 0
	s_nop 0
	s_nop 0
	s_nop 0
	s_nop 0
	s_nop 0
	s_nop 0
	s_nop 0
	s_nop 0
	s_nop 0
	s_nop 0
	s_nop 0
	s_nop 0
	s_nop 0
	s_nop 0
	s_nop 0
	s_load_dwordx2 s[0:1], s[74:75], 0x100
	v_readlane_b32 s2, v251, 10
	v_readlane_b32 s3, v251, 11
	s_waitcnt lgkmcnt(0)
	s_cmp_gt_u32 s1, 6
	s_cselect_b64 s[0:1], -1, 0
	s_and_b64 s[0:1], s[2:3], s[0:1]
	s_andn2_b64 vcc, exec, s[0:1]
	s_cbranch_vccnz .LBB0_617
	s_waitcnt vmcnt(0)
	v_cmp_eq_u32_e32 vcc, 0, v0
	s_barrier
	s_and_saveexec_b64 s[0:1], vcc
	s_cbranch_execz .LBB0_616
	v_readlane_b32 s2, v251, 7
	s_waitcnt vmcnt(0) expcnt(0) lgkmcnt(0)
	s_nop 0
	v_mov_b32_e32 v1, s2
	ds_read_b32 v3, v1
	ds_read_b32 v1, v1 offset:4
	s_waitcnt lgkmcnt(1)
	v_cmp_ne_u32_e32 vcc, 0, v3
	s_cbranch_vccnz .LBB0_584
	v_readlane_b32 s2, v251, 2
	v_readlane_b32 s3, v251, 3
	s_load_dwordx2 s[6:7], s[2:3], 0x4
	s_load_dword s8, s[74:75], 0x108
	s_add_u32 s2, s78, 0x4200
	s_addc_u32 s3, s79, 0
	s_add_u32 s4, s78, 0x4400
	s_addc_u32 s5, s79, 0
	s_waitcnt lgkmcnt(0)
	s_mul_i32 s33, s6, s8
	s_add_u32 s6, s78, 0x4500
	s_mul_i32 s33, s33, s7
	s_addc_u32 s7, s79, 0
	s_add_u32 s8, s78, 0x4600
	s_addc_u32 s9, s79, 0
	s_add_u32 s10, s78, 0x4700
	s_addc_u32 s11, s79, 0
	s_add_u32 s12, s78, 0x4800
	s_addc_u32 s13, s79, 0
	s_add_u32 s14, s78, 0x4900
	s_addc_u32 s15, s79, 0
	s_add_u32 s16, s78, 0x4a00
	s_addc_u32 s17, s79, 0
	s_add_u32 s18, s78, 0x4b00
	s_addc_u32 s19, s79, 0
	s_add_u32 s20, s78, 0x4c00
	s_addc_u32 s21, s79, 0
	s_add_u32 s22, s78, 0x4d00
	s_addc_u32 s23, s79, 0
	s_add_u32 s24, s78, 0x4e00
	s_addc_u32 s25, s79, 0
	s_add_u32 s26, s78, 0x4f00
	s_addc_u32 s27, s79, 0
	s_add_u32 s28, s78, 0x5000
	s_addc_u32 s29, s79, 0
	s_add_u32 s30, s78, 0x5100
	s_addc_u32 s31, s79, 0
	s_add_u32 s34, s78, 0x5200
	s_addc_u32 s35, s79, 0
	s_add_u32 s36, s78, 0x5300
	s_addc_u32 s37, s79, 0
	s_mov_b32 s44, 1
	v_mov_b32_e32 v17, 0
	s_branch .LBB0_572

; __device__ __forceinline__ unsigned xb_add(unsigned* p, unsigned v) { return __hip_atomic_fetch_add(p, v, __ATOMIC_RELAXED, __HIP_MEMORY_SCOPE_AGENT); }
; #define INP(i) ldin(i)
; #define SEAM(k) do { if (IN(k) && IN((k) + 1)) xcd_barrier(bar); } while (0)
; __device__ __forceinline__ void xcd_barrier(const XcdBarrier& b) {
;     asm volatile("s_waitcnt vmcnt(0)" ::: "memory");
;     __syncthreads();
;     if (threadIdx.x == 0) {
;         unsigned* bar = b.bar;
;         __builtin_amdgcn_s_waitcnt(0);
;         unsigned nloc = b.st[0], nx = b.st[1];
;         if (nloc == 0u) { xcd_barrier_complete(bar, b.x, nloc, nx); b.st[0] = nloc; b.st[1] = nx; }
;         const unsigned old = xb_add(&bar[XB_XSUB(b.x)], 1u);
; __global__ void __launch_bounds__(NWAVES * 64, 2) mk_fwd(Args args) {
;     ...
;             if (IN(15)) moba_kv_phase(F, WSP(const bf16, WS_ACT_A), WSP(const bf16, WS_XC + 72 * MiB), WSP(const bf16, WS_XC), WSP(const int, WS_XC + 136 * MiB), WSP(const unsigned short, WS_XC + 138 * MiB), INP(18), INP(19), WSP(bf16, WS_ACT_C), WSP(float, WS_XC + 64 * MiB));
;             SEAM(15);
.LBB0_1681:
	s_setprio 0
	s_nop 0
	s_nop 0
	s_nop 0
	s_nop 0
	s_nop 0
	s_nop 0
	s_nop 0
	s_nop 0
	s_nop 0
	s_nop 0
	s_nop 0
	s_nop 0
	s_nop 0
	s_nop 0
	s_nop 0
	s_nop 0
	s_nop 0
	s_nop 0
	s_nop 0
	s_nop 0
	s_nop 0
	s_nop 0
	s_nop 0
	s_nop 0
	s_nop 0
	s_nop 0
	s_nop 0
	s_nop 0
	s_load_dwordx2 s[0:1], s[74:75], 0x100
	s_waitcnt lgkmcnt(0)
	s_cmp_gt_i32 s1, 16
	s_cselect_b64 s[0:1], -1, 0
	s_and_b64 s[2:3], s[64:65], s[0:1]
	s_andn2_b64 vcc, exec, s[2:3]
	s_cbranch_vccnz .LBB0_1733
	s_waitcnt vmcnt(0)
	v_cmp_eq_u32_e32 vcc, 0, v0
	s_waitcnt vmcnt(0)
	s_barrier
	s_and_saveexec_b64 s[2:3], vcc
	s_cbranch_execz .LBB0_1732
	v_readlane_b32 s4, v251, 7
	s_waitcnt vmcnt(0) expcnt(0) lgkmcnt(0)
	s_nop 0
	v_mov_b32_e32 v1, s4
	ds_read_b32 v3, v1
	ds_read_b32 v1, v1 offset:4
	s_waitcnt lgkmcnt(1)
	v_cmp_ne_u32_e32 vcc, 0, v3
	s_cbranch_vccnz .LBB0_1700
	v_readlane_b32 s4, v251, 2
	v_readlane_b32 s5, v251, 3
	s_load_dwordx2 s[8:9], s[4:5], 0x4
	s_add_u32 s4, s78, 0x4200
	s_addc_u32 s5, s79, 0
	s_add_u32 s6, s78, 0x4400
	s_addc_u32 s7, s79, 0
	v_readlane_b32 s10, v251, 0
	s_waitcnt lgkmcnt(0)
	s_mul_i32 s33, s8, s10
	s_add_u32 s8, s78, 0x4500
	s_mul_i32 s33, s33, s9
	s_addc_u32 s9, s79, 0
	v_readlane_b32 s11, v251, 1
	s_add_u32 s10, s78, 0x4600
	s_addc_u32 s11, s79, 0
	s_add_u32 s12, s78, 0x4700
	s_addc_u32 s13, s79, 0
	s_add_u32 s14, s78, 0x4800
	s_addc_u32 s15, s79, 0
	s_add_u32 s16, s78, 0x4900
	s_addc_u32 s17, s79, 0
	s_add_u32 s18, s78, 0x4a00
	s_addc_u32 s19, s79, 0
	s_add_u32 s20, s78, 0x4b00
	s_addc_u32 s21, s79, 0
	s_add_u32 s22, s78, 0x4c00
	s_addc_u32 s23, s79, 0
	s_add_u32 s24, s78, 0x4d00
	s_addc_u32 s25, s79, 0
	s_add_u32 s26, s78, 0x4e00
	s_addc_u32 s27, s79, 0
	s_add_u32 s28, s78, 0x4f00
	s_addc_u32 s29, s79, 0
	s_add_u32 s30, s78, 0x5000
	s_addc_u32 s31, s79, 0
	s_add_u32 s34, s78, 0x5100
	s_addc_u32 s35, s79, 0
	s_add_u32 s36, s78, 0x5200
	s_addc_u32 s37, s79, 0
	s_add_u32 s38, s78, 0x5300
	s_addc_u32 s39, s79, 0
	s_mov_b32 s46, 1
	v_mov_b32_e32 v17, 0
	s_branch .LBB0_1686

; __device__ __forceinline__ unsigned xb_add(unsigned* p, unsigned v) { return __hip_atomic_fetch_add(p, v, __ATOMIC_RELAXED, __HIP_MEMORY_SCOPE_AGENT); }
; __device__ __forceinline__ void xcd_barrier(const XcdBarrier& b) {
;     asm volatile("s_waitcnt vmcnt(0)" ::: "memory");
;     __syncthreads();
;     if (threadIdx.x == 0) {
;         unsigned* bar = b.bar;
;         __builtin_amdgcn_s_waitcnt(0);
;         unsigned nloc = b.st[0], nx = b.st[1];
;         if (nloc == 0u) { xcd_barrier_complete(bar, b.x, nloc, nx); b.st[0] = nloc; b.st[1] = nx; }
;         const unsigned old = xb_add(&bar[XB_XSUB(b.x)], 1u);
.LBB0_2274:
	s_setprio 0
	s_nop 0
	s_nop 0
	s_nop 0
	s_nop 0
	s_nop 0
	s_nop 0
	s_nop 0
	s_nop 0
	s_nop 0
	s_nop 0
	s_nop 0
	s_nop 0
	s_nop 0
	s_nop 0
	s_nop 0
	s_nop 0
	s_nop 0
	s_nop 0
	s_nop 0
	s_nop 0
	s_nop 0
	s_nop 0
	s_nop 0
	s_nop 0
	s_nop 0
	s_nop 0
	s_nop 0
	s_nop 0
	v_readlane_b32 s0, v251, 4
	v_readlane_b32 s1, v251, 5
	s_cmp_gt_u32 s1, 23
	v_readlane_b32 s2, v252, 13
	s_cselect_b64 s[0:1], -1, 0
	v_readlane_b32 s3, v252, 14
	s_and_b64 s[0:1], s[2:3], s[0:1]
	s_andn2_b64 vcc, exec, s[0:1]
	s_cbranch_vccnz .LBB0_2324
	s_waitcnt vmcnt(0)
	v_cmp_eq_u32_e32 vcc, 0, v0
	s_waitcnt vmcnt(0)
	s_barrier
	s_and_saveexec_b64 s[0:1], vcc
	s_cbranch_execz .LBB0_2323
	v_readlane_b32 s2, v251, 7
	s_waitcnt vmcnt(0) expcnt(0) lgkmcnt(0)
	s_nop 0
	v_mov_b32_e32 v1, s2
	ds_read_b32 v3, v1
	ds_read_b32 v1, v1 offset:4
	s_waitcnt lgkmcnt(1)
	v_cmp_ne_u32_e32 vcc, 0, v3
	s_cbranch_vccnz .LBB0_2291
	v_readlane_b32 s2, v251, 2
	v_readlane_b32 s3, v251, 3
	s_load_dwordx2 s[6:7], s[2:3], 0x4
	s_add_u32 s2, s78, 0x4200
	s_addc_u32 s3, s79, 0
	s_add_u32 s4, s78, 0x4400
	s_addc_u32 s5, s79, 0
	v_readlane_b32 s8, v251, 0
	s_waitcnt lgkmcnt(0)
	s_mul_i32 s33, s6, s8
	s_add_u32 s6, s78, 0x4500
	s_mul_i32 s33, s33, s7
	s_addc_u32 s7, s79, 0
	v_readlane_b32 s9, v251, 1
	s_add_u32 s8, s78, 0x4600
	s_addc_u32 s9, s79, 0
	s_add_u32 s10, s78, 0x4700
	s_addc_u32 s11, s79, 0
	s_add_u32 s12, s78, 0x4800
	s_addc_u32 s13, s79, 0
	s_add_u32 s14, s78, 0x4900
	s_addc_u32 s15, s79, 0
	s_add_u32 s16, s78, 0x4a00
	s_addc_u32 s17, s79, 0
	s_add_u32 s18, s78, 0x4b00
	s_addc_u32 s19, s79, 0
	s_add_u32 s20, s78, 0x4c00
	s_addc_u32 s21, s79, 0
	s_add_u32 s22, s78, 0x4d00
	s_addc_u32 s23, s79, 0
	s_add_u32 s24, s78, 0x4e00
	s_addc_u32 s25, s79, 0
	s_add_u32 s26, s78, 0x4f00
	s_addc_u32 s27, s79, 0
	s_add_u32 s28, s78, 0x5000
	s_addc_u32 s29, s79, 0
	s_add_u32 s30, s78, 0x5100
	s_addc_u32 s31, s79, 0
	s_add_u32 s34, s78, 0x5200
	s_addc_u32 s35, s79, 0
	s_add_u32 s36, s78, 0x5300
	s_addc_u32 s37, s79, 0
	s_mov_b32 s44, 1
	v_mov_b32_e32 v17, 0
	s_branch .LBB0_2279
